# P2b: 16 dwordx2 KVT stores per e-chunk widened to 8 dwordx4 via permlane32/16 swaps (on top of P1 peel)
# speedup vs baseline: 1.0104x; 1.0104x over previous
.LBB0_297:
	s_or_b64 exec, exec, s[0:1]
	v_lshrrev_b32_e32 v18, 4, v68
	v_bfe_u32 v0, v63, 2, 2
	v_lshl_or_b32 v19, v18, 3, v0
	v_bfe_u32 v22, v63, 1, 1
	v_lshrrev_b32_e32 v0, 3, v68
	v_lshl_or_b32 v23, s46, 2, v22
	v_and_b32_e32 v24, 12, v63
	v_and_b32_e32 v25, 2, v0
	v_or_b32_e32 v26, v25, v24
	v_bitop3_b32 v37, v25, v23, v24 bitop3:0x36
	v_lshlrev_b32_e32 v119, 4, v37
	v_bitop3_b32 v37, v26, v23, 1 bitop3:0x36
	v_lshrrev_b32_e32 v21, 1, v63
	v_lshlrev_b32_e32 v120, 4, v37
	v_or_b32_e32 v37, 2, v23
	v_bitop3_b32 v23, v23, v26, 2 bitop3:0x36
	v_lshlrev_b32_e32 v121, 4, v23
	v_bitop3_b32 v23, v26, v37, 1 bitop3:0x36
	v_bitop3_b32 v21, v26, v21, 1 bitop3:0x72
	v_lshlrev_b32_e32 v122, 4, v23
	v_or_b32_e32 v23, v26, v22
	v_lshlrev_b32_e32 v126, 4, v21
	v_or_b32_e32 v21, 2, v22
	v_lshlrev_b32_e32 v125, 4, v23
	v_bitop3_b32 v23, v25, v21, v24 bitop3:0x36
	v_bitop3_b32 v21, v26, v21, 1 bitop3:0x36
	v_lshlrev_b32_e32 v128, 4, v21
	v_or_b32_e32 v21, 4, v22
	v_lshlrev_b32_e32 v127, 4, v23
	v_bitop3_b32 v23, v25, v21, v24 bitop3:0x36
	v_bitop3_b32 v21, v26, v21, 1 bitop3:0x36
	v_lshlrev_b32_e32 v130, 4, v21
	v_or_b32_e32 v21, 6, v22
	v_lshlrev_b32_e32 v129, 4, v23
	v_bitop3_b32 v23, v25, v21, v24 bitop3:0x36
	v_bitop3_b32 v21, v26, v21, 1 bitop3:0x36
	v_lshlrev_b32_e32 v132, 4, v21
	v_or_b32_e32 v21, 8, v22
	s_lshl_b32 s0, s49, 22
	v_lshlrev_b32_e32 v131, 4, v23
	v_bitop3_b32 v23, v25, v21, v24 bitop3:0x36
	v_bitop3_b32 v21, v26, v21, 1 bitop3:0x36
	v_and_b32_e32 v20, 15, v63
	s_add_i32 s4, s0, 0x5900000
	s_lshl_b64 s[0:1], s[20:21], 9
	v_lshlrev_b32_e32 v134, 4, v21
	v_or_b32_e32 v21, 10, v22
	s_add_u32 s2, s50, 0x2c80
	s_add_i32 s5, 0, 0x10000
	v_or_b32_e32 v106, s0, v20
	v_mov_b32_e32 v107, s1
	s_lshl_b64 s[0:1], s[20:21], 17
	v_lshlrev_b32_e32 v133, 4, v23
	v_bitop3_b32 v23, v25, v21, v24 bitop3:0x36
	v_bitop3_b32 v21, v26, v21, 1 bitop3:0x36
	s_cmp_lt_u32 s47, 64
	v_lshlrev_b32_e32 v136, 4, v21
	v_or_b32_e32 v21, 12, v22
	s_cselect_b64 s[16:17], -1, 0
	s_cmp_eq_u32 s46, 1
	v_lshlrev_b32_e32 v135, 4, v23
	v_bitop3_b32 v23, v25, v21, v24 bitop3:0x36
	v_bitop3_b32 v21, v26, v21, 1 bitop3:0x36
	s_cselect_b64 s[72:73], -1, 0
	s_cmp_eq_u32 s46, 2
	v_lshlrev_b32_e32 v138, 4, v21
	v_or_b32_e32 v21, 14, v22
	v_and_b32_e32 v0, 8, v64
	s_cselect_b64 s[64:65], -1, 0
	s_cmp_eq_u32 s46, 3
	v_bitop3_b32 v22, v25, v21, v24 bitop3:0x36
	v_bitop3_b32 v21, v26, v21, 1 bitop3:0x36
	v_add_u32_e32 v27, 0, v0
	v_add_u32_e32 v28, s5, v0
	v_and_b32_e32 v0, 48, v68
	v_lshlrev_b32_e32 v29, 2, v62
	v_lshlrev_b32_e32 v31, 2, v65
	v_lshlrev_b32_e32 v33, 2, v66
	v_lshlrev_b32_e32 v35, 2, v67
	s_cselect_b64 s[74:75], -1, 0
	s_cmp_eq_u32 s46, 4
	v_lshlrev_b32_e32 v140, 4, v21
	v_or_b32_e32 v21, 32, v19
	v_lshl_add_u64 v[108:109], s[52:53], 0, v[0:1]
	v_lshlrev_b32_e32 v0, 3, v18
	v_and_b32_e32 v29, 12, v29
	v_bfe_u32 v30, v62, 2, 2
	v_and_b32_e32 v31, 12, v31
	v_bfe_u32 v32, v65, 2, 2
	v_and_b32_e32 v33, 12, v33
	v_bfe_u32 v34, v66, 2, 2
	v_and_b32_e32 v35, 12, v35
	v_bfe_u32 v36, v67, 2, 2
	s_cselect_b64 s[76:77], -1, 0
	s_cmp_eq_u32 s46, 5
	v_lshlrev_b32_e32 v139, 4, v22
	v_lshl_add_u32 v141, v21, 9, v27
	v_or_b32_e32 v22, 36, v19
	v_lshl_add_u32 v143, v21, 8, v28
	v_or_b32_e32 v21, 64, v19
	v_lshl_or_b32 v18, s46, 5, v0
	v_bitop3_b32 v29, v29, v20, v30 bitop3:0x36
	v_bitop3_b32 v31, v31, v20, v32 bitop3:0x36
	v_bitop3_b32 v33, v33, v20, v34 bitop3:0x36
	v_bitop3_b32 v35, v35, v20, v36 bitop3:0x36
	v_lshl_add_u32 v117, v19, 9, v27
	v_or_b32_e32 v36, 4, v19
	v_lshl_add_u32 v123, v19, 8, v28
	s_cselect_b64 s[78:79], -1, 0
	s_cmp_eq_u32 s46, 6
	v_lshl_add_u32 v142, v22, 9, v27
	v_lshl_add_u32 v144, v22, 8, v28
	v_lshl_add_u32 v145, v21, 9, v27
	v_or_b32_e32 v22, 0x44, v19
	v_lshl_add_u32 v147, v21, 8, v28
	v_or_b32_e32 v21, 0x60, v19
	v_or_b32_e32 v19, 0x64, v19
	v_lshlrev_b32_e32 v0, 8, v62
	v_lshl_add_u32 v29, v29, 4, s5
	v_lshlrev_b32_e32 v30, 8, v65
	v_lshl_add_u32 v31, v31, 4, s5
	v_lshlrev_b32_e32 v32, 8, v66
	v_lshl_add_u32 v33, v33, 4, s5
	v_lshlrev_b32_e32 v34, 8, v67
	v_lshl_add_u32 v35, v35, 4, s5
	s_cselect_b64 s[80:81], -1, 0
	s_cmp_eq_u32 s46, 7
	v_lshl_add_u32 v150, v19, 9, v27
	v_lshl_add_u32 v152, v19, 8, v28
	v_ashrrev_i32_e32 v19, 31, v18
	v_lshl_add_u32 v118, v36, 9, v27
	v_lshl_add_u32 v124, v36, 8, v28
	v_lshlrev_b32_e32 v137, 4, v23
	s_cselect_b64 s[82:83], -1, 0
	v_lshl_add_u32 v146, v22, 9, v27
	v_lshl_add_u32 v148, v22, 8, v28
	v_lshl_add_u32 v149, v21, 9, v27
	v_lshl_add_u32 v151, v21, 8, v28
	v_lshl_add_u64 v[110:111], v[18:19], 1, s[10:11]
	v_lshlrev_b32_e32 v112, 8, v20
	v_mov_b32_e32 v113, v1
	s_mov_b64 s[84:85], 0
	v_add_u32_e32 v153, v29, v0
	v_add_u32_e32 v154, v31, v30
	v_add_u32_e32 v155, v33, v32
	v_add_u32_e32 v156, v35, v34
	s_mov_b64 s[86:87], 0
	s_waitcnt lgkmcnt(0)
	s_barrier
	s_branch .LBB0_299
.LBB0_298:
	s_nop 1
	v_lshl_add_u64 v[72:73], v[112:113], 0, s[84:85]
	s_waitcnt lgkmcnt(0)
	v_mfma_f32_16x16x32_bf16 v[26:29], v[74:77], v[66:69], v[26:29]
	v_or_b32_e32 v75, s1, v73
	v_or_b32_e32 v74, s0, v72
	v_cvt_pk_bf16_f32 v90, v90, v91
	v_cvt_pk_bf16_f32 v91, v92, v93
	v_mfma_f32_16x16x32_bf16 v[22:25], v[78:81], v[66:69], v[22:25]
	v_cvt_pk_bf16_f32 v92, v18, v19
	v_cvt_pk_bf16_f32 v93, v20, v21
	v_lshl_add_u64 v[18:19], v[74:75], 1, v[110:111]
	s_nop 1
	v_permlane32_swap_b32 v90, v92
	v_permlane32_swap_b32 v91, v93
	s_nop 1
	v_permlane16_swap_b32 v90, v92
	v_permlane16_swap_b32 v91, v93
	s_nop 0
	global_store_dwordx4 v[18:19], v[90:93], off
	v_cvt_pk_bf16_f32 v82, v82, v83
	v_cvt_pk_bf16_f32 v83, v84, v85
	v_cvt_pk_bf16_f32 v84, v30, v31
	v_cvt_pk_bf16_f32 v85, v32, v33
	s_mov_b64 s[28:29], 0x1000
	v_lshl_add_u64 v[30:31], v[72:73], 0, s[28:29]
	v_or_b32_e32 v31, s1, v31
	v_or_b32_e32 v30, s0, v30
	v_lshl_add_u64 v[30:31], v[30:31], 1, v[110:111]
	s_nop 1
	v_permlane32_swap_b32 v82, v84
	v_permlane32_swap_b32 v83, v85
	s_nop 1
	v_permlane16_swap_b32 v82, v84
	v_permlane16_swap_b32 v83, v85
	s_nop 0
	global_store_dwordx4 v[30:31], v[82:85], off
	v_cvt_pk_bf16_f32 v86, v86, v87
	v_cvt_pk_bf16_f32 v87, v88, v89
	v_cvt_pk_bf16_f32 v88, v34, v35
	v_cvt_pk_bf16_f32 v89, v36, v37
	s_mov_b64 s[28:29], 0x2000
	v_lshl_add_u64 v[34:35], v[72:73], 0, s[28:29]
	v_or_b32_e32 v35, s1, v35
	v_or_b32_e32 v34, s0, v34
	v_lshl_add_u64 v[34:35], v[34:35], 1, v[110:111]
	s_nop 1
	v_permlane32_swap_b32 v86, v88
	v_permlane32_swap_b32 v87, v89
	s_nop 1
	v_permlane16_swap_b32 v86, v88
	v_permlane16_swap_b32 v87, v89
	s_nop 0
	global_store_dwordx4 v[34:35], v[86:89], off
	v_cvt_pk_bf16_f32 v94, v94, v95
	v_cvt_pk_bf16_f32 v95, v96, v97
	v_cvt_pk_bf16_f32 v96, v38, v39
	v_cvt_pk_bf16_f32 v97, v40, v41
	s_mov_b64 s[28:29], 0x3000
	v_lshl_add_u64 v[38:39], v[72:73], 0, s[28:29]
	v_or_b32_e32 v39, s1, v39
	v_or_b32_e32 v38, s0, v38
	v_lshl_add_u64 v[38:39], v[38:39], 1, v[110:111]
	s_nop 1
	v_permlane32_swap_b32 v94, v96
	v_permlane32_swap_b32 v95, v97
	s_nop 1
	v_permlane16_swap_b32 v94, v96
	v_permlane16_swap_b32 v95, v97
	s_nop 0
	global_store_dwordx4 v[38:39], v[94:97], off
	v_cvt_pk_bf16_f32 v50, v50, v51
	v_cvt_pk_bf16_f32 v51, v52, v53
	v_cvt_pk_bf16_f32 v52, v42, v43
	v_cvt_pk_bf16_f32 v53, v44, v45
	v_lshl_add_u64 v[42:43], v[72:73], 0, s[66:67]
	v_or_b32_e32 v43, s1, v43
	v_or_b32_e32 v42, s0, v42
	v_lshl_add_u64 v[42:43], v[42:43], 1, v[110:111]
	s_nop 1
	v_permlane32_swap_b32 v50, v52
	v_permlane32_swap_b32 v51, v53
	s_nop 1
	v_permlane16_swap_b32 v50, v52
	v_permlane16_swap_b32 v51, v53
	s_nop 0
	global_store_dwordx4 v[42:43], v[50:53], off
	v_cvt_pk_bf16_f32 v58, v58, v59
	v_cvt_pk_bf16_f32 v59, v60, v61
	v_cvt_pk_bf16_f32 v60, v46, v47
	v_cvt_pk_bf16_f32 v61, v48, v49
	s_mov_b64 s[28:29], 0x5000
	v_lshl_add_u64 v[46:47], v[72:73], 0, s[28:29]
	v_or_b32_e32 v47, s1, v47
	v_or_b32_e32 v46, s0, v46
	v_lshl_add_u64 v[46:47], v[46:47], 1, v[110:111]
	s_nop 1
	v_permlane32_swap_b32 v58, v60
	v_permlane32_swap_b32 v59, v61
	s_nop 1
	v_permlane16_swap_b32 v58, v60
	v_permlane16_swap_b32 v59, v61
	s_nop 0
	global_store_dwordx4 v[46:47], v[58:61], off
	v_cvt_pk_bf16_f32 v62, v62, v63
	v_cvt_pk_bf16_f32 v63, v64, v65
	v_cvt_pk_bf16_f32 v64, v54, v55
	v_cvt_pk_bf16_f32 v65, v56, v57
	s_mov_b64 s[28:29], 0x6000
	v_lshl_add_u64 v[54:55], v[72:73], 0, s[28:29]
	v_or_b32_e32 v55, s1, v55
	v_or_b32_e32 v54, s0, v54
	v_lshl_add_u64 v[54:55], v[54:55], 1, v[110:111]
	s_nop 1
	v_permlane32_swap_b32 v62, v64
	v_permlane32_swap_b32 v63, v65
	s_nop 1
	v_permlane16_swap_b32 v62, v64
	v_permlane16_swap_b32 v63, v65
	s_nop 0
	global_store_dwordx4 v[54:55], v[62:65], off
	v_cvt_pk_bf16_f32 v26, v26, v27
	v_cvt_pk_bf16_f32 v27, v28, v29
	v_cvt_pk_bf16_f32 v28, v22, v23
	v_cvt_pk_bf16_f32 v29, v24, v25
	s_mov_b64 s[28:29], 0x7000
	v_lshl_add_u64 v[22:23], v[72:73], 0, s[28:29]
	v_or_b32_e32 v23, s1, v23
	v_or_b32_e32 v22, s0, v22
	v_lshl_add_u64 v[22:23], v[22:23], 1, v[110:111]
	s_nop 1
	v_permlane32_swap_b32 v26, v28
	v_permlane32_swap_b32 v27, v29
	s_nop 1
	v_permlane16_swap_b32 v26, v28
	v_permlane16_swap_b32 v27, v29
	s_nop 0
	global_store_dwordx4 v[22:23], v[26:29], off
	s_add_u32 s86, s86, 0x80
	s_addc_u32 s87, s87, 0
	s_add_i32 s4, s4, 0x100000
	s_add_u32 s84, s84, 0x8000
	s_addc_u32 s85, s85, 0
	s_cmp_lg_u32 s84, 0x20000
	s_cbranch_scc0 .LBB0_284
